# grid barrier release fan-out: WG0 writes the release generation into each workgroup's own control slot, each workgroup polls its own line (on top of v40)
# speedup vs baseline: 1.0006x; 1.0006x over previous
; #define FB_LD(p) __hip_atomic_load((p), __ATOMIC_RELAXED, __HIP_MEMORY_SCOPE_AGENT)
; #define FB_ST(p, v) __hip_atomic_store((p), (v), __ATOMIC_RELAXED, __HIP_MEMORY_SCOPE_AGENT)
; __device__ __forceinline__ void flag_barrier(unsigned* base, unsigned gen) {
;     ...
;         const int c = blockIdx.x, G = gridDim.x, lane = threadIdx.x;
;         __builtin_amdgcn_fence(__ATOMIC_RELEASE, "agent");
;         asm volatile("s_waitcnt vmcnt(0)" ::: "memory");
;         if (lane == 0) FB_ST(base + 64 * (1 + c), gen);
;         if (c == 0) {
;             unsigned sp = 0;
;             for (;;) {
;                 unsigned ok = 1u;
;                 for (int m = lane; m < G; m += 64) ok &= (unsigned)(FB_LD(base + 64 * (1 + m)) >= gen);
;                 if (__all((int)ok)) break;
;                 __builtin_amdgcn_s_sleep(1); if (++sp > (1u << 22)) break;
;             }
;             if (lane == 0) FB_ST(base, gen);
;         }
;         { unsigned sp = 0; while (FB_LD(base) < gen) { __builtin_amdgcn_s_sleep(1); if (++sp > (1u << 22)) break; } }
.LBB0_501:
	s_or_b64 exec, exec, s[8:9]
	v_readlane_b32 s100, v255, 4
	v_readlane_b32 s101, v255, 5
	s_add_u32 s100, s12, s100
	s_addc_u32 s101, s13, s101
	s_add_u32 s100, s100, 0x180
	s_addc_u32 s101, s101, 0
	s_cmpk_eq_i32 s5, 0x100
	s_cselect_b32 s100, s100, s12
	s_cselect_b32 s101, s101, s13
	s_andn2_b64 vcc, exec, s[94:95]
	s_cbranch_vccnz .LBB0_513
	v_cmp_gt_i32_e64 s[8:9], s5, v163
	s_mov_b32 s6, 0
	s_branch .LBB0_504

; #define FB_LD(p) __hip_atomic_load((p), __ATOMIC_RELAXED, __HIP_MEMORY_SCOPE_AGENT)
; #define FB_ST(p, v) __hip_atomic_store((p), (v), __ATOMIC_RELAXED, __HIP_MEMORY_SCOPE_AGENT)
; __device__ __forceinline__ void flag_barrier(unsigned* base, unsigned gen) {
;     ...
;         if (c == 0) {
;             unsigned sp = 0;
;             for (;;) {
;                 unsigned ok = 1u;
;                 for (int m = lane; m < G; m += 64) ok &= (unsigned)(FB_LD(base + 64 * (1 + m)) >= gen);
;                 if (__all((int)ok)) break;
;                 __builtin_amdgcn_s_sleep(1); if (++sp > (1u << 22)) break;
;             }
;             if (lane == 0) FB_ST(base, gen);
.LBB0_510:
	s_cmpk_lg_i32 s5, 0x100
	s_cbranch_scc1 .Lrel_generic
	v_mov_b32_e32 v0, s4
	v_lshlrev_b32_e32 v1, 8, v163
	global_store_dword v1, v0, s[12:13] offset:384 sc1
	v_add_u32_e32 v3, 0x4000, v1
	global_store_dword v3, v0, s[12:13] offset:384 sc1
	v_add_u32_e32 v3, 0x8000, v1
	global_store_dword v3, v0, s[12:13] offset:384 sc1
	v_add_u32_e32 v3, 0xc000, v1
	global_store_dword v3, v0, s[12:13] offset:384 sc1

; #define FB_LD(p) __hip_atomic_load((p), __ATOMIC_RELAXED, __HIP_MEMORY_SCOPE_AGENT)
; __device__ __forceinline__ void flag_barrier(unsigned* base, unsigned gen) {
;     ...
;         { unsigned sp = 0; while (FB_LD(base) < gen) { __builtin_amdgcn_s_sleep(1); if (++sp > (1u << 22)) break; } }
.LBB0_515:
	global_load_dword v0, v145, s[100:101] sc1
	s_mov_b64 s[8:9], -1
	s_waitcnt vmcnt(0)
	v_cmp_le_u32_e32 vcc, s4, v0
	s_cbranch_vccnz .LBB0_514
	s_sleep 1
	global_load_dword v0, v145, s[100:101] sc1
	s_waitcnt vmcnt(0)
	v_cmp_gt_u32_e32 vcc, s4, v0
	s_cbranch_vccz .LBB0_514
	s_sleep 1
	global_load_dword v0, v145, s[100:101] sc1
	s_waitcnt vmcnt(0)
	v_cmp_gt_u32_e32 vcc, s4, v0
	s_cbranch_vccz .LBB0_514
	s_sleep 1
	global_load_dword v0, v145, s[100:101] sc1
	s_waitcnt vmcnt(0)
	v_cmp_gt_u32_e32 vcc, s4, v0
	s_cbranch_vccz .LBB0_514
	s_sleep 1
	global_load_dword v0, v145, s[100:101] sc1
	s_waitcnt vmcnt(0)
	v_cmp_gt_u32_e32 vcc, s4, v0
	s_cbranch_vccz .LBB0_514
	s_add_i32 s5, s5, -5
	s_cmp_eq_u32 s5, 0
	s_cselect_b64 s[8:9], -1, 0
	s_sleep 1
	s_branch .LBB0_514
